# combo14 + E54: in PD half of the CUs (bid bit 5) run their two SSD items before their four mLSTM items, so the chip always works on a mix of both item types
# speedup vs baseline: 1.0102x; 1.0102x over previous
.LBB0_137:
	v_readlane_b32 s0, v251, 47
	v_readlane_b32 s1, v251, 48
	s_andn2_b64 vcc, exec, s[0:1]
	v_readlane_b32 s14, v253, 60
	s_mov_b32 s15, s57
	s_mov_b32 s16, s57
	s_cbranch_vccnz .Lpd_not
	s_movk_i32 s32, 0x7fff
	s_cmpk_lg_u32 s36, 0x100
	s_cbranch_scc1 .LBB0_199
	s_movk_i32 s32, 6
	s_bitcmp1_b32 s57, 5
	s_cbranch_scc0 .LBB0_199
	s_addk_i32 s16, 0x400
	s_addk_i32 s15, 0x400
	s_addk_i32 s14, 0x400
	s_branch .LBB0_199
.Lpd_not:
.LBB0_138:
	s_mov_b64 s[8:9], -1

.LBB0_198:
	s_add_i32 s16, s16, s36
	s_add_i32 s15, s15, s36
	s_add_i32 s14, s14, s36
	s_add_i32 s32, s32, -1
	s_waitcnt lgkmcnt(0)
	s_cmp_eq_u32 s32, 0
	s_cbranch_scc1 .LBB0_138
	s_cmpk_gt_i32 s16, 0x5ff
	s_cbranch_scc0 .LBB0_199
	s_cmpk_gt_u32 s32, 0x1000
	s_cbranch_scc1 .LBB0_138
	s_addk_i32 s16, -1536
	s_addk_i32 s15, -1536
	s_addk_i32 s14, -1536
